# adds: HGRN per-step v-row staging DMA alternates between waves 6 and 7 instead of always wave 7 (on the LDS-transposed SB epilogue version, without the final-norm change)
# speedup vs baseline: 1.0029x; 1.0029x over previous
; #define LAS __attribute__((address_space(3)))
; __device__ __forceinline__ int otid() { int t = threadIdx.x; asm volatile("" : "+v"(t)); return t; }
; __device__ __forceinline__ void load_raw(Raw& R, const bf16_t* qsrc, const bf16_t* fsrc, const bf16_t* vsrc, int step, bool isv) {
;     const size_t o = (size_t)step * 16 * PW;
; #pragma unroll
;     for (int i = 0; i < 4; ++i) { R.q[i] = *(const unsigned*)(qsrc + o + (size_t)i * PW); R.f[i] = *(const unsigned*)(fsrc + o + (size_t)i * PW); R.v[i] = *(const unsigned*)(vsrc + o + (size_t)i * PW); }
; }
; template <bool DRY> __device__ __forceinline__ void hgrn_unit(LAS unsigned char* lds, int b, int h, int vs, int layer, bf16_t* Pm, const float* lbraw) {
;     using namespace hg;
;     const int tid = otid(), lane = tid & 63; const int wid = __builtin_amdgcn_readfirstlane(tid >> 6);
;     const size_t tok0 = (size_t)b * SEQ;
;     const int kl = lane & 15, tq = lane >> 4, kch = 16 * wid + kl;
;     (void)layer; (void)lbraw;
;     const bf16_t* qsrc = Pm + (tok0 + 4 * tq) * PW + PC_HQ + h * 128 + (kch & ~1);
;     const bf16_t* fsrc = Pm + (tok0 + 4 * tq) * PW + PC_HF + h * 128 + (kch & ~1);
;     const bool isv = tid < 128; const int vv = tid & 31, vtq = (tid >> 5) & 3;
;     const bf16_t* vsrc = Pm + (tok0 + 4 * vtq) * PW + PC_HI + h * 128 + vs * 32 + (vv & ~1);
;     constexpr int NSTEP = SEQ / 16;
;     for (int i = tid; i < SB / 4; i += NTHREADS) ((LAS unsigned*)(lds + OFF_S + SB))[i] = 0u;
;     Raw ra, rb;
;     load_raw(ra, qsrc, fsrc, vsrc, 0, isv);
;     prep(ra, lds, lane, kch, tq, isv, vv, vtq);
;     load_raw(ra, qsrc, fsrc, vsrc, 1, isv); load_raw(rb, qsrc, fsrc, vsrc, 2, isv);
;     f32x16 sacc = {};
;     const int c16 = lane & 15, kq = lane >> 4, r32 = lane & 31, hh = lane >> 5;
;     __syncthreads();
.LBB0_615:
	s_or_b64 exec, exec, s[6:7]
	s_ashr_i32 s6, s22, 4
	s_ashr_i32 s7, s6, 31
	v_bfe_u32 v9, v3, 4, 2
	s_lshl_b64 s[14:15], s[6:7], 11
	v_lshlrev_b32_e32 v8, 2, v9
	v_or_b32_e32 v0, s14, v8
	v_mov_b64_e32 v[4:5], s[4:5]
	v_bfe_u32 v12, v3, 5, 2
	s_ashr_i32 s28, s10, 6
	s_mov_b32 s65, s28
	v_mad_u64_u32 v[0:1], s[6:7], v0, s24, v[4:5]
	s_lshl_b32 s10, s22, 5
	v_lshl_or_b32 v6, v12, 2, s14
	s_and_b32 s6, s10, 0x180
	v_mad_u64_u32 v[4:5], s[8:9], v6, s24, v[4:5]
	v_and_b32_e32 v7, 15, v3
	s_lshl_b32 s34, s28, 4
	v_mad_i32_i24 v1, s15, v240, v1
	s_lshl_b32 s6, s6, 1
	s_mov_b32 s7, s29
	v_mad_i32_i24 v5, s15, v240, v5
	v_lshl_add_u64 v[0:1], v[0:1], 0, s[6:7]
	v_bitop3_b32 v10, s34, -2, v7 bitop3:0xc8
	v_lshl_add_u64 v[4:5], v[4:5], 0, s[6:7]
	s_and_b32 s7, s10, 0x60
	v_ashrrev_i32_e32 v11, 31, v10
	s_lshl_b32 s8, s7, 1
	s_mul_i32 s41, s14, 0x1d40
	s_add_u32 s38, s4, s41
	s_addc_u32 s39, s5, 0
	s_add_u32 s38, s38, s6
	s_addc_u32 s39, s39, 0
	s_add_u32 s38, s38, 0xd00
	s_addc_u32 s39, s39, 0
	s_mov_b32 s9, s29
	v_and_b32_e32 v6, 30, v3
	v_lshl_add_u64 v[0:1], v[10:11], 1, v[0:1]
	v_lshl_add_u64 v[4:5], v[4:5], 0, s[8:9]
	v_lshlrev_b32_e32 v10, 1, v6
	v_mov_b32_e32 v11, v2
	s_movk_i32 s7, 0x1000
	v_lshl_add_u64 v[4:5], v[4:5], 0, v[10:11]
	v_add_co_u32_e32 v10, vcc, s7, v0
	v_cmp_eq_u32_e64 s[50:51], 3, v9
	s_nop 0
	v_addc_co_u32_e32 v11, vcc, 0, v1, vcc
	v_add_co_u32_e32 v14, vcc, s7, v4
	s_movk_i32 s7, 0x2000
	s_nop 0
	v_addc_co_u32_e32 v15, vcc, 0, v5, vcc
	v_add_co_u32_e32 v16, vcc, s7, v0
	s_movk_i32 s7, 0x3000
	s_nop 0
	v_addc_co_u32_e32 v17, vcc, 0, v1, vcc
	v_add_co_u32_e32 v18, vcc, s7, v4
	s_movk_i32 s7, 0x4000
	s_nop 0
	v_addc_co_u32_e32 v19, vcc, 0, v5, vcc
	v_add_co_u32_e32 v20, vcc, s7, v0
	s_nop 1
	v_addc_co_u32_e32 v21, vcc, 0, v1, vcc
	s_nop 0
	s_nop 0
	s_nop 0
	s_nop 0
	v_add_co_u32_e32 v10, vcc, s7, v4
	s_movk_i32 s7, 0x6000
	s_nop 0
	v_addc_co_u32_e32 v11, vcc, 0, v5, vcc
	v_add_co_u32_e32 v10, vcc, s7, v0
	s_nop 1
	v_addc_co_u32_e32 v11, vcc, 0, v1, vcc
	v_add_co_u32_e32 v18, vcc, s7, v4
	s_movk_i32 s7, 0x440
	s_nop 0
	v_addc_co_u32_e32 v19, vcc, 0, v5, vcc
	s_nop 0
	v_and_b32_e32 v19, 1, v3
	v_cmp_eq_u32_e64 s[44:45], 0, v19
	v_and_b32_e32 v11, 63, v3
	v_cmp_gt_u32_e64 s[46:47], 16, v11
	v_cmp_lt_u32_e64 s[48:49], 31, v11
	v_or_b32_e32 v10, s34, v7
	v_lshl_add_u32 v36, v10, 1, 0
	v_mad_u32_u24 v42, v9, s7, v36
	v_bfe_u32 v140, v234, 4, 2
	v_mul_u32_u24_e32 v136, 0x440, v140
	v_lshrrev_b32_e32 v140, 6, v234
	v_and_b32_e32 v141, 15, v234
	v_lshl_or_b32 v140, v140, 4, v141
	v_lshrrev_b32_e32 v140, 1, v140
	v_lshl_add_u32 v136, v140, 2, v136
	v_add_u32_e32 v136, 0xd400, v136
	v_bfe_i32 v145, v234, 4, 1
	v_and_b32_e32 v144, 1, v234
	v_lshl_add_u32 v144, v144, 1, v136
	v_bfe_u32 v140, v234, 5, 2
	v_and_b32_e32 v141, 31, v234
	v_lshrrev_b32_e32 v141, 1, v141
	v_lshlrev_b32_e32 v141, 2, v141
	v_lshl_add_u32 v137, v140, 8, v141
	v_add_u32_e32 v137, 0xf600, v137
	v_and_b32_e32 v140, 63, v234
	v_lshrrev_b32_e32 v141, 4, v140
	v_lshrrev_b32_e32 v142, 6, v234
	v_and_b32_e32 v143, 3, v142
	v_lshl_add_u32 v141, v143, 2, v141
	v_mul_u32_u24_e32 v138, 0x1d40, v141
	v_and_b32_e32 v141, 15, v140
	v_lshl_add_u32 v138, v141, 4, v138
	v_lshrrev_b32_e32 v142, 2, v142
	v_lshl_add_u32 v138, v142, 10, v138
	v_lshrrev_b32_e32 v141, 2, v140
	v_mul_u32_u24_e32 v139, 0x1d40, v141
	v_and_b32_e32 v141, 3, v140
	v_lshl_add_u32 v139, v141, 4, v139
	v_add_u32_e32 v139, 0x800, v139
	v_add_u32_e32 v139, s8, v139
	s_mul_i32 s64, s65, 0x440
	s_add_i32 s64, s64, 0xd400
	s_mov_b64 s[42:43], s[38:39]
	s_cmp_lt_u32 s65, 6
	s_cbranch_scc1 .Lhg_pro_nov
	s_add_i32 m0, s64, 0
	s_nop 0
	global_load_lds_dwordx4 v138, s[42:43]
	s_cmp_lg_u32 s65, 7
	s_cbranch_scc1 .Lhg_pro_sk0
	s_mov_b32 m0, 0xf600
	s_nop 0
	global_load_lds_dwordx4 v139, s[42:43]
.Lhg_pro_sk0:
	s_add_u32 s42, s42, 0x1d400
	s_addc_u32 s43, s43, 0
	s_add_i32 m0, s64, 9792
	s_nop 0
	global_load_lds_dwordx4 v138, s[42:43]
	s_cmp_lg_u32 s65, 6
	s_cbranch_scc1 .Lhg_pro_sk1
	s_mov_b32 m0, 0x11c40
	s_nop 0
	global_load_lds_dwordx4 v139, s[42:43]
.Lhg_pro_sk1:
	s_add_u32 s42, s42, 0x1d400
	s_addc_u32 s43, s43, 0
	s_add_i32 m0, s64, 19584
	s_nop 0
	global_load_lds_dwordx4 v138, s[42:43]
	s_cmp_lg_u32 s65, 7
	s_cbranch_scc1 .Lhg_pro_sk2
	s_mov_b32 m0, 0x14280
	s_nop 0
	global_load_lds_dwordx4 v139, s[42:43]
.Lhg_pro_sk2:
	s_add_u32 s42, s42, 0x1d400
	s_addc_u32 s43, s43, 0
	s_add_i32 m0, s64, 29376
	s_nop 0
	global_load_lds_dwordx4 v138, s[42:43]
	s_cmp_lg_u32 s65, 6
	s_cbranch_scc1 .Lhg_pro_sk3
	s_mov_b32 m0, 0x168c0
	s_nop 0
	global_load_lds_dwordx4 v139, s[42:43]
.Lhg_pro_sk3:
	s_waitcnt vmcnt(3)
	s_branch .Lhg_pro_done

; template <bool DRY> __device__ __forceinline__ void hgrn_unit(LAS unsigned char* lds, int b, int h, int vs, int layer, bf16_t* Pm, const float* lbraw) {
;     ...
; #pragma unroll 1
;     for (int g8 = 0; g8 < NSTEP; g8 += 8) {
; #pragma unroll 1
;         for (int n2 = g8; n2 < g8 + 8; n2 += 2) {
;             { const int n = n2; HG_STEP(n, ra); }
;             { const int n = n2 + 1; HG_STEP(n, rb); }
.LBB0_624:
	s_waitcnt lgkmcnt(0)
	s_cmp_ge_u32 s65, 6
	s_cbranch_scc1 .Lhg_w7_b
	s_waitcnt vmcnt(2)
	s_branch .Lhg_wd_b
.Lhg_w7_b:
	s_waitcnt vmcnt(3)

.Lhg_wd_a:
	s_barrier
	s_cmpk_gt_u32 s7, 0x7d
	s_cbranch_scc1 .LBB0_642
	s_add_i32 s41, s7, 5
	s_min_u32 s41, s41, 0x7f
	s_mul_i32 s41, s41, 0x1d400
	s_add_u32 s42, s38, s41
	s_addc_u32 s43, s39, 0
	s_add_i32 s41, s7, 1
	s_and_b32 s41, s41, 3
	s_mul_i32 s41, s41, 9792
	s_add_i32 m0, s41, s64
	s_nop 0
	global_load_lds_dwordx4 v138, s[42:43]
	s_cmp_lg_u32 s65, 6
	s_cbranch_scc1 .Lhg_nov_b
	s_add_i32 m0, s41, 0xf600
	s_nop 0
	global_load_lds_dwordx4 v139, s[42:43]
